# ret_state unit: K/V tile loads issued together (8 in flight) and LDS writes deferred past the decay-weight math, instead of load-wait-write ladder
# baseline (speedup 1.0000x reference)
.LBB0_1036:
	s_andn2_b64 vcc, exec, s[6:7]
	s_cbranch_vccnz .LBB0_1045
	s_add_i32 s6, s86, 0xfffffa70
	v_mov_b32_e32 v25, v228
	s_lshr_b32 s17, s6, 2
	s_load_dwordx2 s[6:7], s[0:1], 0x70
	s_and_b32 s16, s86, 3
	s_lshl_b32 s8, s45, 3
	s_or_b32 s8, s8, s16
	s_ashr_i32 s9, s8, 31
	s_lshl_b64 s[8:9], s[8:9], 2
	s_waitcnt lgkmcnt(0)
	s_add_u32 s6, s6, s8
	s_addc_u32 s7, s7, s9
	global_load_dword v0, v65, s[6:7]
	global_load_dword v2, v65, s[6:7] offset:16
	s_mov_b32 s8, 0x3f2aaaab
	s_barrier
	s_waitcnt vmcnt(0)
	v_mul_f32_e32 v0, 0xbfb8aa3b, v0
	v_exp_f32_e32 v1, v0
	s_nop 0
	v_add_f32_e32 v3, 1.0, v1
	v_frexp_mant_f32_e32 v0, v3
	v_cmp_gt_f32_e64 s[6:7], s8, v0
	v_mul_f32_e32 v0, 0xbfb8aa3b, v2
	v_exp_f32_e32 v0, v0
	s_nop 0
	v_add_f32_e32 v2, 1.0, v0
	v_frexp_mant_f32_e32 v4, v2
	v_cmp_gt_f32_e32 vcc, s8, v4
	s_movk_i32 s8, 0x800
	v_cmp_gt_i32_e64 s[8:9], s8, v25
	s_and_saveexec_b64 s[10:11], s[8:9]
	s_cbranch_execz .LBB0_1040
	s_load_dwordx2 s[8:9], s[0:1], 0x100
	s_lshl_b32 s18, s17, 8
	s_lshl_b32 s12, s16, 7
	v_lshlrev_b32_e32 v4, 3, v25
	s_mov_b64 s[14:15], 0
	s_waitcnt lgkmcnt(0)
	s_add_u32 s8, s8, s12
	s_addc_u32 s9, s9, 0
	s_add_u32 s12, s8, 0xae00000
	s_addc_u32 s13, s9, 0
	v_mov_b32_e32 v5, v25
	v_ashrrev_i32_e32 v12, 3, v5
	v_add_u32_e32 v8, s18, v12
	v_mov_b64_e32 v[6:7], s[12:13]
	v_mad_i64_i32 v[6:7], s[8:9], v8, s93, v[6:7]
	v_lshlrev_b32_e32 v8, 1, v4
	v_and_b32_e32 v64, 0x70, v8
	v_lshl_add_u64 v[10:11], v[6:7], 0, v[64:65]
	s_mov_b64 s[20:21], 0x58000
	v_lshlrev_b32_e32 v12, 7, v12
	global_load_dwordx4 v[88:91], v[10:11], off offset:512
	global_load_dwordx4 v[92:95], v[10:11], off offset:1024
	v_lshl_add_u64 v[6:7], v[10:11], 0, s[20:21]
	v_add3_u32 v116, 0, v12, v64
	global_load_dwordx4 v[96:99], v[6:7], off offset:512
	global_load_dwordx4 v[100:103], v[6:7], off offset:1024
	v_lshl_add_u64 v[10:11], v[6:7], 0, s[20:21]
	s_nop 0
	global_load_dwordx4 v[104:107], v[10:11], off offset:512
	global_load_dwordx4 v[108:111], v[10:11], off offset:1024
	v_lshl_add_u64 v[6:7], v[10:11], 0, s[20:21]
	s_nop 0
	global_load_dwordx4 v[112:115], v[6:7], off offset:512
	global_load_dwordx4 v[148:151], v[6:7], off offset:1024

.LBB0_1042:
	s_or_b64 exec, exec, s[6:7]
	s_waitcnt vmcnt(7)
	ds_write_b128 v116, v[88:91]
	s_waitcnt vmcnt(6)
	ds_write_b128 v116, v[92:95] offset:32768
	s_waitcnt vmcnt(5)
	ds_write_b128 v116, v[96:99] offset:8192
	s_waitcnt vmcnt(4)
	ds_write_b128 v116, v[100:103] offset:40960
	s_waitcnt vmcnt(3)
	ds_write_b128 v116, v[104:107] offset:16384
	s_waitcnt vmcnt(2)
	ds_write_b128 v116, v[108:111] offset:49152
	s_waitcnt vmcnt(1)
	ds_write_b128 v116, v[112:115] offset:24576
	s_waitcnt vmcnt(0)
	ds_write_b128 v116, v[148:151] offset:57344
	v_ashrrev_i32_e32 v27, 3, v25
	v_and_b32_e32 v0, 7, v25
	v_mov_b32_e32 v1, 0x8000
	v_mov_b32_e32 v8, 0
	v_lshl_or_b32 v32, v0, 4, v1
	v_lshlrev_b32_e32 v33, 1, v27
	s_mov_b32 s6, 0
	v_mov_b32_e32 v9, v8
	v_mov_b32_e32 v10, v8
	v_mov_b32_e32 v11, v8
	v_mov_b32_e32 v4, v8
	v_mov_b32_e32 v5, v8
	v_mov_b32_e32 v6, v8
	v_mov_b32_e32 v7, v8
	v_mov_b32_e32 v12, v8
	v_mov_b32_e32 v13, v8
	v_mov_b32_e32 v14, v8
	v_mov_b32_e32 v15, v8
	v_mov_b32_e32 v0, v8
	v_mov_b32_e32 v1, v8
	v_mov_b32_e32 v2, v8
	v_mov_b32_e32 v3, v8
	s_waitcnt lgkmcnt(0)
	s_barrier
